# Hyena: channels assigned so the 32 workgroups of one XCD class handle the 64 adjacent channels of each 128-byte line of H (whole-line assembly in one L2)
# speedup vs baseline: 1.0134x; 1.0025x over previous
.LBB0_106:
	s_mov_b32 s0, s2
	v_mov_b32_e32 v0, v196
	s_and_b32 s1, s0, 7
	s_lshl_b32 s1, s1, 6
	s_lshr_b32 s0, s0, 3
	s_lshl_b32 s0, s0, 1
	s_add_i32 s0, s0, s1
	v_readfirstlane_b32 s1, v0
	s_ashr_i32 s1, s1, 8
	v_mov_b32_e32 v0, v196
	s_add_i32 s1, s1, s0
	s_nop 0
	v_readfirstlane_b32 s0, v0
	s_ashr_i32 s0, s0, 8
	s_sub_i32 s51, s1, s0
	s_cmpk_gt_i32 s51, 0x7ff
	s_cbranch_scc1 .LBB0_357
	s_mul_i32 s0, s55, 0x9000
	s_lshl_b32 s88, s55, 11
	s_add_u32 s89, s78, s0
	s_mul_i32 s1, s55, 0x3000
	s_addc_u32 s90, s79, 0
	s_add_u32 s91, s80, s1
	s_addc_u32 s92, s81, 0
	s_add_i32 s95, s94, 16
	s_add_i32 s50, s95, 0x1100
	s_add_i32 s54, s95, 0x1330
	s_add_i32 s95, s95, 0x8100
	s_branch .LBB0_110
